# GEMM K loops: priority 1 after the first MFMA, 3 from MFMA 16 until the barrier (the wave closer to its barrier wins the SIMD)
# baseline (speedup 1.0000x reference)
.Lgq_c:
	ds_read_b128 v[114:117], v188 offset:16384
	ds_read_b128 v[118:121], v188 offset:16896
	ds_read_b128 v[156:159], v188 offset:20480
	ds_read_b128 v[160:163], v188 offset:20992
	ds_read_b128 v[122:125], v112
	ds_read_b128 v[126:129], v112 offset:2048
	s_waitcnt lgkmcnt(1)
	v_mfma_f32_16x16x32_bf16 v[66:69], v[114:117], v[122:125], v[66:69]
	s_setprio 1
	global_load_dwordx4 v[62:65], v216, s[0:1] offset:256
	v_mfma_f32_16x16x32_bf16 v[58:61], v[118:121], v[122:125], v[58:61]
	s_waitcnt vmcnt(8)
	ds_write_b128 v110, v[224:227] offset:32768
	v_mfma_f32_16x16x32_bf16 v[54:57], v[156:159], v[122:125], v[54:57]
	v_mfma_f32_16x16x32_bf16 v[50:53], v[160:163], v[122:125], v[50:53]
	global_load_dwordx4 v[70:73], v217, s[0:1] offset:256
	s_waitcnt lgkmcnt(1)
	v_mfma_f32_16x16x32_bf16 v[46:49], v[114:117], v[126:129], v[46:49]
	ds_read_b128 v[180:183], v112 offset:4096
	ds_read_b128 v[184:187], v112 offset:6144
	v_mfma_f32_16x16x32_bf16 v[42:45], v[118:121], v[126:129], v[42:45]
	s_waitcnt vmcnt(8)
	ds_write_b128 v110, v[228:231] offset:36864
	v_mfma_f32_16x16x32_bf16 v[38:41], v[156:159], v[126:129], v[38:41]
	global_load_dwordx4 v[74:77], v218, s[0:1] offset:256
	v_mfma_f32_16x16x32_bf16 v[34:37], v[160:163], v[126:129], v[34:37]
	s_waitcnt lgkmcnt(2)
	v_mfma_f32_16x16x32_bf16 v[30:33], v[114:117], v[180:183], v[30:33]
	ds_read_b128 v[164:167], v189 offset:16384
	ds_read_b128 v[168:171], v189 offset:16896
	v_mfma_f32_16x16x32_bf16 v[26:29], v[118:121], v[180:183], v[26:29]
	global_load_dwordx4 v[78:81], v219, s[0:1] offset:256
	v_mfma_f32_16x16x32_bf16 v[22:25], v[156:159], v[180:183], v[22:25]
	ds_read_b128 v[172:175], v189 offset:20480
	ds_read_b128 v[176:179], v189 offset:20992
	v_mfma_f32_16x16x32_bf16 v[18:21], v[160:163], v[180:183], v[18:21]
	s_waitcnt vmcnt(9)
	ds_write_b128 v110, v[232:235] offset:40960
	s_waitcnt lgkmcnt(6)
	v_mfma_f32_16x16x32_bf16 v[14:17], v[114:117], v[184:187], v[14:17]
	ds_read_b128 v[122:125], v113
	ds_read_b128 v[126:129], v113 offset:2048
	v_mfma_f32_16x16x32_bf16 v[10:13], v[118:121], v[184:187], v[10:13]
	global_load_dwordx4 v[82:85], v216, s[6:7] offset:256
	v_mfma_f32_16x16x32_bf16 v[6:9], v[156:159], v[184:187], v[6:9]
	s_waitcnt vmcnt(9)
	ds_write_b128 v110, v[236:239] offset:45056
	v_mfma_f32_16x16x32_bf16 v[2:5], v[160:163], v[184:187], v[2:5]
	s_setprio 3
	s_waitcnt lgkmcnt(2)
	v_mfma_f32_16x16x32_bf16 v[66:69], v[164:167], v[122:125], v[66:69]
	global_load_dwordx4 v[86:89], v217, s[6:7] offset:256
	v_mfma_f32_16x16x32_bf16 v[58:61], v[168:171], v[122:125], v[58:61]
	s_waitcnt vmcnt(9)
	ds_write_b128 v190, v[240:243] offset:49168
	v_mfma_f32_16x16x32_bf16 v[54:57], v[172:175], v[122:125], v[54:57]
	v_mfma_f32_16x16x32_bf16 v[50:53], v[176:179], v[122:125], v[50:53]
	global_load_dwordx4 v[90:93], v218, s[6:7] offset:256
	s_waitcnt lgkmcnt(2)
	v_mfma_f32_16x16x32_bf16 v[46:49], v[164:167], v[126:129], v[46:49]
	ds_read_b128 v[180:183], v113 offset:4096
	ds_read_b128 v[184:187], v113 offset:6144
	v_mfma_f32_16x16x32_bf16 v[42:45], v[168:171], v[126:129], v[42:45]
	s_waitcnt vmcnt(9)
	ds_write_b128 v190, v[244:247] offset:53264
	v_mfma_f32_16x16x32_bf16 v[38:41], v[172:175], v[126:129], v[38:41]
	global_load_dwordx4 v[94:97], v219, s[6:7] offset:256
	v_mfma_f32_16x16x32_bf16 v[34:37], v[176:179], v[126:129], v[34:37]
	s_waitcnt lgkmcnt(2)
	v_mfma_f32_16x16x32_bf16 v[30:33], v[164:167], v[180:183], v[30:33]
	s_waitcnt vmcnt(9)
	ds_write_b128 v190, v[248:251] offset:57360
	v_mfma_f32_16x16x32_bf16 v[26:29], v[168:171], v[180:183], v[26:29]
	v_mfma_f32_16x16x32_bf16 v[22:25], v[172:175], v[180:183], v[22:25]
	v_mfma_f32_16x16x32_bf16 v[18:21], v[176:179], v[180:183], v[18:21]
	s_waitcnt vmcnt(8)
	ds_write_b128 v190, v[252:255] offset:61456
	s_waitcnt lgkmcnt(3)
	v_mfma_f32_16x16x32_bf16 v[14:17], v[164:167], v[184:187], v[14:17]
	v_mfma_f32_16x16x32_bf16 v[10:13], v[168:171], v[184:187], v[10:13]
	v_mfma_f32_16x16x32_bf16 v[6:9], v[172:175], v[184:187], v[6:9]
	v_mfma_f32_16x16x32_bf16 v[2:5], v[176:179], v[184:187], v[2:5]
	s_setprio 0
	s_waitcnt lgkmcnt(0)
	s_barrier
	s_add_u32 s0, s0, 0x80
	s_addc_u32 s1, s1, 0
	s_add_u32 s6, s6, 0x80
	s_addc_u32 s7, s7, 0
	ds_read_b128 v[114:117], v188 offset:49168
	ds_read_b128 v[118:121], v188 offset:49680
	ds_read_b128 v[156:159], v188 offset:53264
	ds_read_b128 v[160:163], v188 offset:53776
	ds_read_b128 v[122:125], v112 offset:32768
	ds_read_b128 v[126:129], v112 offset:34816
	s_waitcnt lgkmcnt(1)
	v_mfma_f32_16x16x32_bf16 v[66:69], v[114:117], v[122:125], v[66:69]
	s_setprio 1
	global_load_dwordx4 v[224:227], v216, s[0:1] offset:256
	v_mfma_f32_16x16x32_bf16 v[58:61], v[118:121], v[122:125], v[58:61]
	s_waitcnt vmcnt(8)
	ds_write_b128 v110, v[62:65]
	v_mfma_f32_16x16x32_bf16 v[54:57], v[156:159], v[122:125], v[54:57]
	v_mfma_f32_16x16x32_bf16 v[50:53], v[160:163], v[122:125], v[50:53]
	global_load_dwordx4 v[228:231], v217, s[0:1] offset:256
	s_waitcnt lgkmcnt(1)
	v_mfma_f32_16x16x32_bf16 v[46:49], v[114:117], v[126:129], v[46:49]
	ds_read_b128 v[180:183], v112 offset:36864
	ds_read_b128 v[184:187], v112 offset:38912
	v_mfma_f32_16x16x32_bf16 v[42:45], v[118:121], v[126:129], v[42:45]
	s_waitcnt vmcnt(8)
	ds_write_b128 v110, v[70:73] offset:4096
	v_mfma_f32_16x16x32_bf16 v[38:41], v[156:159], v[126:129], v[38:41]
	global_load_dwordx4 v[232:235], v218, s[0:1] offset:256
	v_mfma_f32_16x16x32_bf16 v[34:37], v[160:163], v[126:129], v[34:37]
	s_waitcnt lgkmcnt(2)
	v_mfma_f32_16x16x32_bf16 v[30:33], v[114:117], v[180:183], v[30:33]
	ds_read_b128 v[164:167], v189 offset:49168
	ds_read_b128 v[168:171], v189 offset:49680
	v_mfma_f32_16x16x32_bf16 v[26:29], v[118:121], v[180:183], v[26:29]
	global_load_dwordx4 v[236:239], v219, s[0:1] offset:256
	v_mfma_f32_16x16x32_bf16 v[22:25], v[156:159], v[180:183], v[22:25]
	ds_read_b128 v[172:175], v189 offset:53264
	ds_read_b128 v[176:179], v189 offset:53776
	v_mfma_f32_16x16x32_bf16 v[18:21], v[160:163], v[180:183], v[18:21]
	s_waitcnt vmcnt(9)
	ds_write_b128 v110, v[74:77] offset:8192
	s_waitcnt lgkmcnt(6)
	v_mfma_f32_16x16x32_bf16 v[14:17], v[114:117], v[184:187], v[14:17]
	ds_read_b128 v[122:125], v113 offset:32768
	ds_read_b128 v[126:129], v113 offset:34816
	v_mfma_f32_16x16x32_bf16 v[10:13], v[118:121], v[184:187], v[10:13]
	global_load_dwordx4 v[240:243], v216, s[6:7] offset:256
	v_mfma_f32_16x16x32_bf16 v[6:9], v[156:159], v[184:187], v[6:9]
	s_waitcnt vmcnt(9)
	ds_write_b128 v110, v[78:81] offset:12288
	v_mfma_f32_16x16x32_bf16 v[2:5], v[160:163], v[184:187], v[2:5]
	s_setprio 3
	s_waitcnt lgkmcnt(2)
	v_mfma_f32_16x16x32_bf16 v[66:69], v[164:167], v[122:125], v[66:69]
	global_load_dwordx4 v[244:247], v217, s[6:7] offset:256
	v_mfma_f32_16x16x32_bf16 v[58:61], v[168:171], v[122:125], v[58:61]
	s_waitcnt vmcnt(9)
	ds_write_b128 v190, v[82:85] offset:16384
	v_mfma_f32_16x16x32_bf16 v[54:57], v[172:175], v[122:125], v[54:57]
	v_mfma_f32_16x16x32_bf16 v[50:53], v[176:179], v[122:125], v[50:53]
	global_load_dwordx4 v[248:251], v218, s[6:7] offset:256
	s_waitcnt lgkmcnt(2)
	v_mfma_f32_16x16x32_bf16 v[46:49], v[164:167], v[126:129], v[46:49]
	ds_read_b128 v[180:183], v113 offset:36864
	ds_read_b128 v[184:187], v113 offset:38912
	v_mfma_f32_16x16x32_bf16 v[42:45], v[168:171], v[126:129], v[42:45]
	s_waitcnt vmcnt(9)
	ds_write_b128 v190, v[86:89] offset:20480
	v_mfma_f32_16x16x32_bf16 v[38:41], v[172:175], v[126:129], v[38:41]
	global_load_dwordx4 v[252:255], v219, s[6:7] offset:256
	v_mfma_f32_16x16x32_bf16 v[34:37], v[176:179], v[126:129], v[34:37]
	s_waitcnt lgkmcnt(2)
	v_mfma_f32_16x16x32_bf16 v[30:33], v[164:167], v[180:183], v[30:33]
	s_waitcnt vmcnt(9)
	ds_write_b128 v190, v[90:93] offset:24576
	v_mfma_f32_16x16x32_bf16 v[26:29], v[168:171], v[180:183], v[26:29]
	v_mfma_f32_16x16x32_bf16 v[22:25], v[172:175], v[180:183], v[22:25]
	v_mfma_f32_16x16x32_bf16 v[18:21], v[176:179], v[180:183], v[18:21]
	s_waitcnt vmcnt(8)
	ds_write_b128 v190, v[94:97] offset:28672
	s_waitcnt lgkmcnt(3)
	v_mfma_f32_16x16x32_bf16 v[14:17], v[164:167], v[184:187], v[14:17]
	v_mfma_f32_16x16x32_bf16 v[10:13], v[168:171], v[184:187], v[10:13]
	v_mfma_f32_16x16x32_bf16 v[6:9], v[172:175], v[184:187], v[6:9]
	v_mfma_f32_16x16x32_bf16 v[2:5], v[176:179], v[184:187], v[2:5]
	s_setprio 0
	s_waitcnt lgkmcnt(0)
	s_barrier
	s_add_u32 s0, s0, 0x80
	s_addc_u32 s1, s1, 0
	s_add_u32 s6, s6, 0x80
	s_addc_u32 s7, s7, 0
	s_sub_i32 vcc_lo, vcc_lo, 1
	s_cmp_lg_u32 vcc_lo, 0
	s_cbranch_scc1 .Lgq_c
	ds_read_b128 v[114:117], v188 offset:16384
	ds_read_b128 v[118:121], v188 offset:16896
	ds_read_b128 v[156:159], v188 offset:20480
	ds_read_b128 v[160:163], v188 offset:20992
	ds_read_b128 v[122:125], v112
	ds_read_b128 v[126:129], v112 offset:2048
	s_waitcnt lgkmcnt(1)
	v_mfma_f32_16x16x32_bf16 v[66:69], v[114:117], v[122:125], v[66:69]
	s_setprio 1
	v_mfma_f32_16x16x32_bf16 v[58:61], v[118:121], v[122:125], v[58:61]
	s_waitcnt vmcnt(7)
	ds_write_b128 v110, v[224:227] offset:32768
	v_mfma_f32_16x16x32_bf16 v[54:57], v[156:159], v[122:125], v[54:57]
	v_mfma_f32_16x16x32_bf16 v[50:53], v[160:163], v[122:125], v[50:53]
	s_waitcnt lgkmcnt(1)
	v_mfma_f32_16x16x32_bf16 v[46:49], v[114:117], v[126:129], v[46:49]
	ds_read_b128 v[180:183], v112 offset:4096
	ds_read_b128 v[184:187], v112 offset:6144
	v_mfma_f32_16x16x32_bf16 v[42:45], v[118:121], v[126:129], v[42:45]
	s_waitcnt vmcnt(6)
	ds_write_b128 v110, v[228:231] offset:36864
	v_mfma_f32_16x16x32_bf16 v[38:41], v[156:159], v[126:129], v[38:41]
	v_mfma_f32_16x16x32_bf16 v[34:37], v[160:163], v[126:129], v[34:37]
	s_waitcnt lgkmcnt(2)
	v_mfma_f32_16x16x32_bf16 v[30:33], v[114:117], v[180:183], v[30:33]
	ds_read_b128 v[164:167], v189 offset:16384
	ds_read_b128 v[168:171], v189 offset:16896
	v_mfma_f32_16x16x32_bf16 v[26:29], v[118:121], v[180:183], v[26:29]
	v_mfma_f32_16x16x32_bf16 v[22:25], v[156:159], v[180:183], v[22:25]
	ds_read_b128 v[172:175], v189 offset:20480
	ds_read_b128 v[176:179], v189 offset:20992
	v_mfma_f32_16x16x32_bf16 v[18:21], v[160:163], v[180:183], v[18:21]
	s_waitcnt vmcnt(5)
	ds_write_b128 v110, v[232:235] offset:40960
	s_waitcnt lgkmcnt(6)
	v_mfma_f32_16x16x32_bf16 v[14:17], v[114:117], v[184:187], v[14:17]
	ds_read_b128 v[122:125], v113
	ds_read_b128 v[126:129], v113 offset:2048
	v_mfma_f32_16x16x32_bf16 v[10:13], v[118:121], v[184:187], v[10:13]
	v_mfma_f32_16x16x32_bf16 v[6:9], v[156:159], v[184:187], v[6:9]
	s_waitcnt vmcnt(4)
	ds_write_b128 v110, v[236:239] offset:45056
	v_mfma_f32_16x16x32_bf16 v[2:5], v[160:163], v[184:187], v[2:5]
	s_setprio 3
	s_waitcnt lgkmcnt(2)
	v_mfma_f32_16x16x32_bf16 v[66:69], v[164:167], v[122:125], v[66:69]
	v_mfma_f32_16x16x32_bf16 v[58:61], v[168:171], v[122:125], v[58:61]
	s_waitcnt vmcnt(3)
	ds_write_b128 v190, v[240:243] offset:49168
	v_mfma_f32_16x16x32_bf16 v[54:57], v[172:175], v[122:125], v[54:57]
	v_mfma_f32_16x16x32_bf16 v[50:53], v[176:179], v[122:125], v[50:53]
	s_waitcnt lgkmcnt(2)
	v_mfma_f32_16x16x32_bf16 v[46:49], v[164:167], v[126:129], v[46:49]
	ds_read_b128 v[180:183], v113 offset:4096
	ds_read_b128 v[184:187], v113 offset:6144
	v_mfma_f32_16x16x32_bf16 v[42:45], v[168:171], v[126:129], v[42:45]
	s_waitcnt vmcnt(2)
	ds_write_b128 v190, v[244:247] offset:53264
	v_mfma_f32_16x16x32_bf16 v[38:41], v[172:175], v[126:129], v[38:41]
	v_mfma_f32_16x16x32_bf16 v[34:37], v[176:179], v[126:129], v[34:37]
	s_waitcnt lgkmcnt(2)
	v_mfma_f32_16x16x32_bf16 v[30:33], v[164:167], v[180:183], v[30:33]
	s_waitcnt vmcnt(1)
	ds_write_b128 v190, v[248:251] offset:57360
	v_mfma_f32_16x16x32_bf16 v[26:29], v[168:171], v[180:183], v[26:29]
	v_mfma_f32_16x16x32_bf16 v[22:25], v[172:175], v[180:183], v[22:25]
	v_mfma_f32_16x16x32_bf16 v[18:21], v[176:179], v[180:183], v[18:21]
	s_waitcnt vmcnt(0)
	ds_write_b128 v190, v[252:255] offset:61456
	s_waitcnt lgkmcnt(3)
	v_mfma_f32_16x16x32_bf16 v[14:17], v[164:167], v[184:187], v[14:17]
	v_mfma_f32_16x16x32_bf16 v[10:13], v[168:171], v[184:187], v[10:13]
	v_mfma_f32_16x16x32_bf16 v[6:9], v[172:175], v[184:187], v[6:9]
	v_mfma_f32_16x16x32_bf16 v[2:5], v[176:179], v[184:187], v[2:5]
	s_waitcnt lgkmcnt(0)
	s_barrier
	ds_read_b128 v[114:117], v188 offset:49168
	ds_read_b128 v[118:121], v188 offset:49680
	ds_read_b128 v[156:159], v188 offset:53264
	ds_read_b128 v[160:163], v188 offset:53776
	ds_read_b128 v[122:125], v112 offset:32768
	ds_read_b128 v[126:129], v112 offset:34816
	s_waitcnt lgkmcnt(1)
	v_mfma_f32_16x16x32_bf16 v[66:69], v[114:117], v[122:125], v[66:69]
	s_setprio 1
	v_mfma_f32_16x16x32_bf16 v[58:61], v[118:121], v[122:125], v[58:61]
	v_mfma_f32_16x16x32_bf16 v[54:57], v[156:159], v[122:125], v[54:57]
	v_mfma_f32_16x16x32_bf16 v[50:53], v[160:163], v[122:125], v[50:53]
	s_waitcnt lgkmcnt(0)
	v_mfma_f32_16x16x32_bf16 v[46:49], v[114:117], v[126:129], v[46:49]
	ds_read_b128 v[180:183], v112 offset:36864
	ds_read_b128 v[184:187], v112 offset:38912
	v_mfma_f32_16x16x32_bf16 v[42:45], v[118:121], v[126:129], v[42:45]
	v_mfma_f32_16x16x32_bf16 v[38:41], v[156:159], v[126:129], v[38:41]
	v_mfma_f32_16x16x32_bf16 v[34:37], v[160:163], v[126:129], v[34:37]
	s_waitcnt lgkmcnt(1)
	v_mfma_f32_16x16x32_bf16 v[30:33], v[114:117], v[180:183], v[30:33]
	ds_read_b128 v[164:167], v189 offset:49168
	ds_read_b128 v[168:171], v189 offset:49680
	v_mfma_f32_16x16x32_bf16 v[26:29], v[118:121], v[180:183], v[26:29]
	v_mfma_f32_16x16x32_bf16 v[22:25], v[156:159], v[180:183], v[22:25]
	ds_read_b128 v[172:175], v189 offset:53264
	ds_read_b128 v[176:179], v189 offset:53776
	v_mfma_f32_16x16x32_bf16 v[18:21], v[160:163], v[180:183], v[18:21]
	s_waitcnt lgkmcnt(4)
	v_mfma_f32_16x16x32_bf16 v[14:17], v[114:117], v[184:187], v[14:17]
	ds_read_b128 v[122:125], v113 offset:32768
	ds_read_b128 v[126:129], v113 offset:34816
	v_mfma_f32_16x16x32_bf16 v[10:13], v[118:121], v[184:187], v[10:13]
	v_mfma_f32_16x16x32_bf16 v[6:9], v[156:159], v[184:187], v[6:9]
	v_mfma_f32_16x16x32_bf16 v[2:5], v[160:163], v[184:187], v[2:5]
	s_setprio 3
	s_waitcnt lgkmcnt(1)
	v_mfma_f32_16x16x32_bf16 v[66:69], v[164:167], v[122:125], v[66:69]
	v_mfma_f32_16x16x32_bf16 v[58:61], v[168:171], v[122:125], v[58:61]
	v_mfma_f32_16x16x32_bf16 v[54:57], v[172:175], v[122:125], v[54:57]
	v_mfma_f32_16x16x32_bf16 v[50:53], v[176:179], v[122:125], v[50:53]
	s_waitcnt lgkmcnt(0)
	v_mfma_f32_16x16x32_bf16 v[46:49], v[164:167], v[126:129], v[46:49]
	ds_read_b128 v[180:183], v113 offset:36864
	ds_read_b128 v[184:187], v113 offset:38912
	v_mfma_f32_16x16x32_bf16 v[42:45], v[168:171], v[126:129], v[42:45]
	v_mfma_f32_16x16x32_bf16 v[38:41], v[172:175], v[126:129], v[38:41]
	v_mfma_f32_16x16x32_bf16 v[34:37], v[176:179], v[126:129], v[34:37]
	s_waitcnt lgkmcnt(1)
	v_mfma_f32_16x16x32_bf16 v[30:33], v[164:167], v[180:183], v[30:33]
	v_mfma_f32_16x16x32_bf16 v[26:29], v[168:171], v[180:183], v[26:29]
	v_mfma_f32_16x16x32_bf16 v[22:25], v[172:175], v[180:183], v[22:25]
	v_mfma_f32_16x16x32_bf16 v[18:21], v[176:179], v[180:183], v[18:21]
	s_waitcnt lgkmcnt(0)
	v_mfma_f32_16x16x32_bf16 v[14:17], v[164:167], v[184:187], v[14:17]
	v_mfma_f32_16x16x32_bf16 v[10:13], v[168:171], v[184:187], v[10:13]
	v_mfma_f32_16x16x32_bf16 v[6:9], v[172:175], v[184:187], v[6:9]
	v_mfma_f32_16x16x32_bf16 v[2:5], v[176:179], v[184:187], v[2:5]
	s_setprio 0
	s_barrier

.Lgq_o:
	ds_read_b128 v[114:117], v188 offset:16384
	ds_read_b128 v[122:125], v188 offset:16896
	ds_read_b128 v[126:129], v188 offset:20480
	ds_read_b128 v[156:159], v188 offset:20992
	ds_read_b128 v[118:121], v112
	ds_read_b128 v[160:163], v112 offset:2048
	s_waitcnt lgkmcnt(1)
	v_mfma_f32_16x16x32_bf16 v[94:97], v[114:117], v[118:121], v[94:97]
	s_setprio 1
	global_load_dwordx4 v[2:5], v216, s[10:11] offset:256
	v_mfma_f32_16x16x32_bf16 v[90:93], v[122:125], v[118:121], v[90:93]
	s_waitcnt vmcnt(8)
	ds_write_b128 v108, v[224:227] offset:32768
	v_mfma_f32_16x16x32_bf16 v[86:89], v[126:129], v[118:121], v[86:89]
	v_mfma_f32_16x16x32_bf16 v[82:85], v[156:159], v[118:121], v[82:85]
	global_load_dwordx4 v[6:9], v217, s[10:11] offset:256
	s_waitcnt lgkmcnt(1)
	v_mfma_f32_16x16x32_bf16 v[78:81], v[114:117], v[160:163], v[78:81]
	ds_read_b128 v[180:183], v112 offset:4096
	ds_read_b128 v[184:187], v112 offset:6144
	v_mfma_f32_16x16x32_bf16 v[74:77], v[122:125], v[160:163], v[74:77]
	s_waitcnt vmcnt(8)
	ds_write_b128 v108, v[228:231] offset:36864
	v_mfma_f32_16x16x32_bf16 v[70:73], v[126:129], v[160:163], v[70:73]
	global_load_dwordx4 v[10:13], v218, s[10:11] offset:256
	v_mfma_f32_16x16x32_bf16 v[66:69], v[156:159], v[160:163], v[66:69]
	s_waitcnt lgkmcnt(2)
	v_mfma_f32_16x16x32_bf16 v[62:65], v[114:117], v[180:183], v[62:65]
	ds_read_b128 v[164:167], v189 offset:16384
	ds_read_b128 v[168:171], v189 offset:16896
	v_mfma_f32_16x16x32_bf16 v[58:61], v[122:125], v[180:183], v[58:61]
	global_load_dwordx4 v[14:17], v219, s[10:11] offset:256
	v_mfma_f32_16x16x32_bf16 v[54:57], v[126:129], v[180:183], v[54:57]
	ds_read_b128 v[172:175], v189 offset:20480
	ds_read_b128 v[176:179], v189 offset:20992
	v_mfma_f32_16x16x32_bf16 v[50:53], v[156:159], v[180:183], v[50:53]
	s_waitcnt vmcnt(9)
	ds_write_b128 v108, v[232:235] offset:40960
	s_waitcnt lgkmcnt(6)
	v_mfma_f32_16x16x32_bf16 v[46:49], v[114:117], v[184:187], v[46:49]
	ds_read_b128 v[118:121], v113
	ds_read_b128 v[160:163], v113 offset:2048
	v_mfma_f32_16x16x32_bf16 v[42:45], v[122:125], v[184:187], v[42:45]
	global_load_dwordx4 v[18:21], v216, s[28:29] offset:256
	v_mfma_f32_16x16x32_bf16 v[38:41], v[126:129], v[184:187], v[38:41]
	s_waitcnt vmcnt(9)
	ds_write_b128 v108, v[236:239] offset:45056
	v_mfma_f32_16x16x32_bf16 v[34:37], v[156:159], v[184:187], v[34:37]
	s_setprio 3
	s_waitcnt lgkmcnt(2)
	v_mfma_f32_16x16x32_bf16 v[94:97], v[164:167], v[118:121], v[94:97]
	global_load_dwordx4 v[22:25], v217, s[28:29] offset:256
	v_mfma_f32_16x16x32_bf16 v[90:93], v[168:171], v[118:121], v[90:93]
	s_waitcnt vmcnt(9)
	ds_write_b128 v190, v[240:243] offset:49168
	v_mfma_f32_16x16x32_bf16 v[86:89], v[172:175], v[118:121], v[86:89]
	v_mfma_f32_16x16x32_bf16 v[82:85], v[176:179], v[118:121], v[82:85]
	global_load_dwordx4 v[26:29], v218, s[28:29] offset:256
	s_waitcnt lgkmcnt(2)
	v_mfma_f32_16x16x32_bf16 v[78:81], v[164:167], v[160:163], v[78:81]
	ds_read_b128 v[180:183], v113 offset:4096
	ds_read_b128 v[184:187], v113 offset:6144
	v_mfma_f32_16x16x32_bf16 v[74:77], v[168:171], v[160:163], v[74:77]
	s_waitcnt vmcnt(9)
	ds_write_b128 v190, v[244:247] offset:53264
	v_mfma_f32_16x16x32_bf16 v[70:73], v[172:175], v[160:163], v[70:73]
	global_load_dwordx4 v[30:33], v219, s[28:29] offset:256
	v_mfma_f32_16x16x32_bf16 v[66:69], v[176:179], v[160:163], v[66:69]
	s_waitcnt lgkmcnt(2)
	v_mfma_f32_16x16x32_bf16 v[62:65], v[164:167], v[180:183], v[62:65]
	s_waitcnt vmcnt(9)
	ds_write_b128 v190, v[248:251] offset:57360
	v_mfma_f32_16x16x32_bf16 v[58:61], v[168:171], v[180:183], v[58:61]
	v_mfma_f32_16x16x32_bf16 v[54:57], v[172:175], v[180:183], v[54:57]
	v_mfma_f32_16x16x32_bf16 v[50:53], v[176:179], v[180:183], v[50:53]
	s_waitcnt vmcnt(8)
	ds_write_b128 v190, v[252:255] offset:61456
	s_waitcnt lgkmcnt(3)
	v_mfma_f32_16x16x32_bf16 v[46:49], v[164:167], v[184:187], v[46:49]
	v_mfma_f32_16x16x32_bf16 v[42:45], v[168:171], v[184:187], v[42:45]
	v_mfma_f32_16x16x32_bf16 v[38:41], v[172:175], v[184:187], v[38:41]
	v_mfma_f32_16x16x32_bf16 v[34:37], v[176:179], v[184:187], v[34:37]
	s_setprio 0
	s_waitcnt lgkmcnt(0)
	s_barrier
	s_add_u32 s10, s10, 0x80
	s_addc_u32 s11, s11, 0
	s_add_u32 s28, s28, 0x80
	s_addc_u32 s29, s29, 0
	ds_read_b128 v[114:117], v188 offset:49168
	ds_read_b128 v[122:125], v188 offset:49680
	ds_read_b128 v[126:129], v188 offset:53264
	ds_read_b128 v[156:159], v188 offset:53776
	ds_read_b128 v[118:121], v112 offset:32768
	ds_read_b128 v[160:163], v112 offset:34816
	s_waitcnt lgkmcnt(1)
	v_mfma_f32_16x16x32_bf16 v[94:97], v[114:117], v[118:121], v[94:97]
	s_setprio 1
	global_load_dwordx4 v[224:227], v216, s[10:11] offset:256
	v_mfma_f32_16x16x32_bf16 v[90:93], v[122:125], v[118:121], v[90:93]
	s_waitcnt vmcnt(8)
	ds_write_b128 v108, v[2:5]
	v_mfma_f32_16x16x32_bf16 v[86:89], v[126:129], v[118:121], v[86:89]
	v_mfma_f32_16x16x32_bf16 v[82:85], v[156:159], v[118:121], v[82:85]
	global_load_dwordx4 v[228:231], v217, s[10:11] offset:256
	s_waitcnt lgkmcnt(1)
	v_mfma_f32_16x16x32_bf16 v[78:81], v[114:117], v[160:163], v[78:81]
	ds_read_b128 v[180:183], v112 offset:36864
	ds_read_b128 v[184:187], v112 offset:38912
	v_mfma_f32_16x16x32_bf16 v[74:77], v[122:125], v[160:163], v[74:77]
	s_waitcnt vmcnt(8)
	ds_write_b128 v108, v[6:9] offset:4096
	v_mfma_f32_16x16x32_bf16 v[70:73], v[126:129], v[160:163], v[70:73]
	global_load_dwordx4 v[232:235], v218, s[10:11] offset:256
	v_mfma_f32_16x16x32_bf16 v[66:69], v[156:159], v[160:163], v[66:69]
	s_waitcnt lgkmcnt(2)
	v_mfma_f32_16x16x32_bf16 v[62:65], v[114:117], v[180:183], v[62:65]
	ds_read_b128 v[164:167], v189 offset:49168
	ds_read_b128 v[168:171], v189 offset:49680
	v_mfma_f32_16x16x32_bf16 v[58:61], v[122:125], v[180:183], v[58:61]
	global_load_dwordx4 v[236:239], v219, s[10:11] offset:256
	v_mfma_f32_16x16x32_bf16 v[54:57], v[126:129], v[180:183], v[54:57]
	ds_read_b128 v[172:175], v189 offset:53264
	ds_read_b128 v[176:179], v189 offset:53776
	v_mfma_f32_16x16x32_bf16 v[50:53], v[156:159], v[180:183], v[50:53]
	s_waitcnt vmcnt(9)
	ds_write_b128 v108, v[10:13] offset:8192
	s_waitcnt lgkmcnt(6)
	v_mfma_f32_16x16x32_bf16 v[46:49], v[114:117], v[184:187], v[46:49]
	ds_read_b128 v[118:121], v113 offset:32768
	ds_read_b128 v[160:163], v113 offset:34816
	v_mfma_f32_16x16x32_bf16 v[42:45], v[122:125], v[184:187], v[42:45]
	global_load_dwordx4 v[240:243], v216, s[28:29] offset:256
	v_mfma_f32_16x16x32_bf16 v[38:41], v[126:129], v[184:187], v[38:41]
	s_waitcnt vmcnt(9)
	ds_write_b128 v108, v[14:17] offset:12288
	v_mfma_f32_16x16x32_bf16 v[34:37], v[156:159], v[184:187], v[34:37]
	s_setprio 3
	s_waitcnt lgkmcnt(2)
	v_mfma_f32_16x16x32_bf16 v[94:97], v[164:167], v[118:121], v[94:97]
	global_load_dwordx4 v[244:247], v217, s[28:29] offset:256
	v_mfma_f32_16x16x32_bf16 v[90:93], v[168:171], v[118:121], v[90:93]
	s_waitcnt vmcnt(9)
	ds_write_b128 v190, v[18:21] offset:16384
	v_mfma_f32_16x16x32_bf16 v[86:89], v[172:175], v[118:121], v[86:89]
	v_mfma_f32_16x16x32_bf16 v[82:85], v[176:179], v[118:121], v[82:85]
	global_load_dwordx4 v[248:251], v218, s[28:29] offset:256
	s_waitcnt lgkmcnt(2)
	v_mfma_f32_16x16x32_bf16 v[78:81], v[164:167], v[160:163], v[78:81]
	ds_read_b128 v[180:183], v113 offset:36864
	ds_read_b128 v[184:187], v113 offset:38912
	v_mfma_f32_16x16x32_bf16 v[74:77], v[168:171], v[160:163], v[74:77]
	s_waitcnt vmcnt(9)
	ds_write_b128 v190, v[22:25] offset:20480
	v_mfma_f32_16x16x32_bf16 v[70:73], v[172:175], v[160:163], v[70:73]
	global_load_dwordx4 v[252:255], v219, s[28:29] offset:256
	v_mfma_f32_16x16x32_bf16 v[66:69], v[176:179], v[160:163], v[66:69]
	s_waitcnt lgkmcnt(2)
	v_mfma_f32_16x16x32_bf16 v[62:65], v[164:167], v[180:183], v[62:65]
	s_waitcnt vmcnt(9)
	ds_write_b128 v190, v[26:29] offset:24576
	v_mfma_f32_16x16x32_bf16 v[58:61], v[168:171], v[180:183], v[58:61]
	v_mfma_f32_16x16x32_bf16 v[54:57], v[172:175], v[180:183], v[54:57]
	v_mfma_f32_16x16x32_bf16 v[50:53], v[176:179], v[180:183], v[50:53]
	s_waitcnt vmcnt(8)
	ds_write_b128 v190, v[30:33] offset:28672
	s_waitcnt lgkmcnt(3)
	v_mfma_f32_16x16x32_bf16 v[46:49], v[164:167], v[184:187], v[46:49]
	v_mfma_f32_16x16x32_bf16 v[42:45], v[168:171], v[184:187], v[42:45]
	v_mfma_f32_16x16x32_bf16 v[38:41], v[172:175], v[184:187], v[38:41]
	v_mfma_f32_16x16x32_bf16 v[34:37], v[176:179], v[184:187], v[34:37]
	s_setprio 0
	s_waitcnt lgkmcnt(0)
	s_barrier
	s_add_u32 s10, s10, 0x80
	s_addc_u32 s11, s11, 0
	s_add_u32 s28, s28, 0x80
	s_addc_u32 s29, s29, 0
	s_sub_i32 vcc_lo, vcc_lo, 1
	s_cmp_lg_u32 vcc_lo, 0
	s_cbranch_scc1 .Lgq_o
	ds_read_b128 v[114:117], v188 offset:16384
	ds_read_b128 v[122:125], v188 offset:16896
	ds_read_b128 v[126:129], v188 offset:20480
	ds_read_b128 v[156:159], v188 offset:20992
	ds_read_b128 v[118:121], v112
	ds_read_b128 v[160:163], v112 offset:2048
	s_waitcnt lgkmcnt(1)
	v_mfma_f32_16x16x32_bf16 v[94:97], v[114:117], v[118:121], v[94:97]
	s_setprio 1
	v_mfma_f32_16x16x32_bf16 v[90:93], v[122:125], v[118:121], v[90:93]
	s_waitcnt vmcnt(7)
	ds_write_b128 v108, v[224:227] offset:32768
	v_mfma_f32_16x16x32_bf16 v[86:89], v[126:129], v[118:121], v[86:89]
	v_mfma_f32_16x16x32_bf16 v[82:85], v[156:159], v[118:121], v[82:85]
	s_waitcnt lgkmcnt(1)
	v_mfma_f32_16x16x32_bf16 v[78:81], v[114:117], v[160:163], v[78:81]
	ds_read_b128 v[180:183], v112 offset:4096
	ds_read_b128 v[184:187], v112 offset:6144
	v_mfma_f32_16x16x32_bf16 v[74:77], v[122:125], v[160:163], v[74:77]
	s_waitcnt vmcnt(6)
	ds_write_b128 v108, v[228:231] offset:36864
	v_mfma_f32_16x16x32_bf16 v[70:73], v[126:129], v[160:163], v[70:73]
	v_mfma_f32_16x16x32_bf16 v[66:69], v[156:159], v[160:163], v[66:69]
	s_waitcnt lgkmcnt(2)
	v_mfma_f32_16x16x32_bf16 v[62:65], v[114:117], v[180:183], v[62:65]
	ds_read_b128 v[164:167], v189 offset:16384
	ds_read_b128 v[168:171], v189 offset:16896
	v_mfma_f32_16x16x32_bf16 v[58:61], v[122:125], v[180:183], v[58:61]
	v_mfma_f32_16x16x32_bf16 v[54:57], v[126:129], v[180:183], v[54:57]
	ds_read_b128 v[172:175], v189 offset:20480
	ds_read_b128 v[176:179], v189 offset:20992
	v_mfma_f32_16x16x32_bf16 v[50:53], v[156:159], v[180:183], v[50:53]
	s_waitcnt vmcnt(5)
	ds_write_b128 v108, v[232:235] offset:40960
	s_waitcnt lgkmcnt(6)
	v_mfma_f32_16x16x32_bf16 v[46:49], v[114:117], v[184:187], v[46:49]
	ds_read_b128 v[118:121], v113
	ds_read_b128 v[160:163], v113 offset:2048
	v_mfma_f32_16x16x32_bf16 v[42:45], v[122:125], v[184:187], v[42:45]
	v_mfma_f32_16x16x32_bf16 v[38:41], v[126:129], v[184:187], v[38:41]
	s_waitcnt vmcnt(4)
	ds_write_b128 v108, v[236:239] offset:45056
	v_mfma_f32_16x16x32_bf16 v[34:37], v[156:159], v[184:187], v[34:37]
	s_setprio 3
	s_waitcnt lgkmcnt(2)
	v_mfma_f32_16x16x32_bf16 v[94:97], v[164:167], v[118:121], v[94:97]
	v_mfma_f32_16x16x32_bf16 v[90:93], v[168:171], v[118:121], v[90:93]
	s_waitcnt vmcnt(3)
	ds_write_b128 v190, v[240:243] offset:49168
	v_mfma_f32_16x16x32_bf16 v[86:89], v[172:175], v[118:121], v[86:89]
	v_mfma_f32_16x16x32_bf16 v[82:85], v[176:179], v[118:121], v[82:85]
	s_waitcnt lgkmcnt(2)
	v_mfma_f32_16x16x32_bf16 v[78:81], v[164:167], v[160:163], v[78:81]
	ds_read_b128 v[180:183], v113 offset:4096
	ds_read_b128 v[184:187], v113 offset:6144
	v_mfma_f32_16x16x32_bf16 v[74:77], v[168:171], v[160:163], v[74:77]
	s_waitcnt vmcnt(2)
	ds_write_b128 v190, v[244:247] offset:53264
	v_mfma_f32_16x16x32_bf16 v[70:73], v[172:175], v[160:163], v[70:73]
	v_mfma_f32_16x16x32_bf16 v[66:69], v[176:179], v[160:163], v[66:69]
	s_waitcnt lgkmcnt(2)
	v_mfma_f32_16x16x32_bf16 v[62:65], v[164:167], v[180:183], v[62:65]
	s_waitcnt vmcnt(1)
	ds_write_b128 v190, v[248:251] offset:57360
	v_mfma_f32_16x16x32_bf16 v[58:61], v[168:171], v[180:183], v[58:61]
	v_mfma_f32_16x16x32_bf16 v[54:57], v[172:175], v[180:183], v[54:57]
	v_mfma_f32_16x16x32_bf16 v[50:53], v[176:179], v[180:183], v[50:53]
	s_waitcnt vmcnt(0)
	ds_write_b128 v190, v[252:255] offset:61456
	s_waitcnt lgkmcnt(3)
	v_mfma_f32_16x16x32_bf16 v[46:49], v[164:167], v[184:187], v[46:49]
	v_mfma_f32_16x16x32_bf16 v[42:45], v[168:171], v[184:187], v[42:45]
	v_mfma_f32_16x16x32_bf16 v[38:41], v[172:175], v[184:187], v[38:41]
	v_mfma_f32_16x16x32_bf16 v[34:37], v[176:179], v[184:187], v[34:37]
	s_waitcnt lgkmcnt(0)
	s_barrier
	ds_read_b128 v[114:117], v188 offset:49168
	ds_read_b128 v[122:125], v188 offset:49680
	ds_read_b128 v[126:129], v188 offset:53264
	ds_read_b128 v[156:159], v188 offset:53776
	ds_read_b128 v[118:121], v112 offset:32768
	ds_read_b128 v[160:163], v112 offset:34816
	s_waitcnt lgkmcnt(1)
	v_mfma_f32_16x16x32_bf16 v[94:97], v[114:117], v[118:121], v[94:97]
	s_setprio 1
	v_mfma_f32_16x16x32_bf16 v[90:93], v[122:125], v[118:121], v[90:93]
	v_mfma_f32_16x16x32_bf16 v[86:89], v[126:129], v[118:121], v[86:89]
	v_mfma_f32_16x16x32_bf16 v[82:85], v[156:159], v[118:121], v[82:85]
	s_waitcnt lgkmcnt(0)
	v_mfma_f32_16x16x32_bf16 v[78:81], v[114:117], v[160:163], v[78:81]
	ds_read_b128 v[180:183], v112 offset:36864
	ds_read_b128 v[184:187], v112 offset:38912
	v_mfma_f32_16x16x32_bf16 v[74:77], v[122:125], v[160:163], v[74:77]
	v_mfma_f32_16x16x32_bf16 v[70:73], v[126:129], v[160:163], v[70:73]
	v_mfma_f32_16x16x32_bf16 v[66:69], v[156:159], v[160:163], v[66:69]
	s_waitcnt lgkmcnt(1)
	v_mfma_f32_16x16x32_bf16 v[62:65], v[114:117], v[180:183], v[62:65]
	ds_read_b128 v[164:167], v189 offset:49168
	ds_read_b128 v[168:171], v189 offset:49680
	v_mfma_f32_16x16x32_bf16 v[58:61], v[122:125], v[180:183], v[58:61]
	v_mfma_f32_16x16x32_bf16 v[54:57], v[126:129], v[180:183], v[54:57]
	ds_read_b128 v[172:175], v189 offset:53264
	ds_read_b128 v[176:179], v189 offset:53776
	v_mfma_f32_16x16x32_bf16 v[50:53], v[156:159], v[180:183], v[50:53]
	s_waitcnt lgkmcnt(4)
	v_mfma_f32_16x16x32_bf16 v[46:49], v[114:117], v[184:187], v[46:49]
	ds_read_b128 v[118:121], v113 offset:32768
	ds_read_b128 v[160:163], v113 offset:34816
	v_mfma_f32_16x16x32_bf16 v[42:45], v[122:125], v[184:187], v[42:45]
	v_mfma_f32_16x16x32_bf16 v[38:41], v[126:129], v[184:187], v[38:41]
	v_mfma_f32_16x16x32_bf16 v[34:37], v[156:159], v[184:187], v[34:37]
	s_setprio 3
	s_waitcnt lgkmcnt(1)
	v_mfma_f32_16x16x32_bf16 v[94:97], v[164:167], v[118:121], v[94:97]
	v_mfma_f32_16x16x32_bf16 v[90:93], v[168:171], v[118:121], v[90:93]
	v_mfma_f32_16x16x32_bf16 v[86:89], v[172:175], v[118:121], v[86:89]
	v_mfma_f32_16x16x32_bf16 v[82:85], v[176:179], v[118:121], v[82:85]
	s_waitcnt lgkmcnt(0)
	v_mfma_f32_16x16x32_bf16 v[78:81], v[164:167], v[160:163], v[78:81]
	ds_read_b128 v[180:183], v113 offset:36864
	ds_read_b128 v[184:187], v113 offset:38912
	v_mfma_f32_16x16x32_bf16 v[74:77], v[168:171], v[160:163], v[74:77]
	v_mfma_f32_16x16x32_bf16 v[70:73], v[172:175], v[160:163], v[70:73]
	v_mfma_f32_16x16x32_bf16 v[66:69], v[176:179], v[160:163], v[66:69]
	s_waitcnt lgkmcnt(1)
	v_mfma_f32_16x16x32_bf16 v[62:65], v[164:167], v[180:183], v[62:65]
	v_mfma_f32_16x16x32_bf16 v[58:61], v[168:171], v[180:183], v[58:61]
	v_mfma_f32_16x16x32_bf16 v[54:57], v[172:175], v[180:183], v[54:57]
	v_mfma_f32_16x16x32_bf16 v[50:53], v[176:179], v[180:183], v[50:53]
	s_waitcnt lgkmcnt(0)
	v_mfma_f32_16x16x32_bf16 v[46:49], v[164:167], v[184:187], v[46:49]
	v_mfma_f32_16x16x32_bf16 v[42:45], v[168:171], v[184:187], v[42:45]
	v_mfma_f32_16x16x32_bf16 v[38:41], v[172:175], v[184:187], v[38:41]
	v_mfma_f32_16x16x32_bf16 v[34:37], v[176:179], v[184:187], v[34:37]
	s_setprio 0
	s_barrier
	s_branch .LBB0_1383
